# P5 lazy-rescale threshold test: sub+mul folded into one fmamk on the persistent exp bias, fast-path alpha init moved into the permlane wait slot
# speedup vs baseline: 1.0026x; 1.0012x over previous
; __device__ __forceinline__ void partialSM(f32x16& p0, f32x16& p1, float& m_reg, float& mn, float& alpha) {
;     float pmax = p0[0];
; #pragma unroll
;     for (int r = 1; r < 16; ++r) pmax = fmaxf(pmax, p0[r]);
; #pragma unroll
;     for (int r = 0; r < 16; ++r) pmax = fmaxf(pmax, p1[r]);
;     { auto rr = __builtin_amdgcn_permlane32_swap(__float_as_uint(pmax), __float_as_uint(pmax), false, false);
;       pmax = fmaxf(__uint_as_float(rr[0]), __uint_as_float(rr[1])); }
;     constexpr float C2 = 1.4426950408889634f * SCALE;
;     if (__builtin_expect(__all((pmax - m_reg) * SCALE <= THR), 1)) { mn = m_reg; alpha = 1.f; }
;     else { mn = fmaxf(m_reg, pmax); alpha = __builtin_amdgcn_exp2f((m_reg - mn) * C2); m_reg = mn; }
.Lp5_k2_done:
	s_waitcnt lgkmcnt(0)
	s_barrier
	s_nop 0
	s_waitcnt vmcnt(4)
	v_lshrrev_b32_e32 v160, v163, v146
	v_lshrrev_b32_e32 v161, v163, v147
	v_bfe_i32 v146, v160, 0, 1
	v_bfe_i32 v147, v161, 0, 1
	v_bitop3_b32 v146, v66, s74, v146 bitop3:0xe4
	v_bitop3_b32 v66, v82, s74, v147 bitop3:0xe4
	v_bfe_i32 v82, v160, 1, 1
	v_bfe_i32 v147, v161, 1, 1
	v_bitop3_b32 v82, v67, s74, v82 bitop3:0xe4
	v_bitop3_b32 v67, v83, s74, v147 bitop3:0xe4
	v_bfe_i32 v83, v160, 2, 1
	v_bfe_i32 v147, v161, 2, 1
	v_bitop3_b32 v83, v68, s74, v83 bitop3:0xe4
	v_bitop3_b32 v68, v84, s74, v147 bitop3:0xe4
	v_bfe_i32 v84, v160, 3, 1
	v_bfe_i32 v148, v161, 3, 1
	v_bitop3_b32 v147, v69, s74, v84 bitop3:0xe4
	v_bfe_i32 v84, v160, 8, 1
	v_bitop3_b32 v69, v85, s74, v148 bitop3:0xe4
	v_bfe_i32 v85, v161, 8, 1
	v_bitop3_b32 v148, v70, s74, v84 bitop3:0xe4
	v_bfe_i32 v84, v160, 9, 1
	v_bitop3_b32 v70, v86, s74, v85 bitop3:0xe4
	v_bfe_i32 v85, v161, 9, 1
	v_bitop3_b32 v149, v71, s74, v84 bitop3:0xe4
	v_bfe_i32 v84, v160, 10, 1
	v_bitop3_b32 v71, v87, s74, v85 bitop3:0xe4
	v_bfe_i32 v85, v161, 10, 1
	v_bitop3_b32 v87, v72, s74, v84 bitop3:0xe4
	v_bfe_i32 v84, v160, 11, 1
	v_bitop3_b32 v72, v88, s74, v85 bitop3:0xe4
	v_bfe_i32 v85, v161, 11, 1
	v_bitop3_b32 v88, v73, s74, v84 bitop3:0xe4
	v_bfe_i32 v73, v160, 16, 1
	v_bitop3_b32 v84, v89, s74, v85 bitop3:0xe4
	v_bfe_i32 v85, v161, 16, 1
	v_bitop3_b32 v89, v74, s74, v73 bitop3:0xe4
	v_bfe_i32 v73, v160, 17, 1
	v_bfe_i32 v74, v161, 17, 1
	v_bitop3_b32 v85, v90, s74, v85 bitop3:0xe4
	v_bitop3_b32 v90, v75, s74, v73 bitop3:0xe4
	v_bitop3_b32 v86, v91, s74, v74 bitop3:0xe4
	v_bfe_i32 v73, v160, 18, 1
	v_bfe_i32 v74, v161, 18, 1
	v_bitop3_b32 v91, v76, s74, v73 bitop3:0xe4
	v_bitop3_b32 v76, v92, s74, v74 bitop3:0xe4
	v_bfe_i32 v73, v160, 19, 1
	v_bfe_i32 v74, v161, 19, 1
	v_bitop3_b32 v92, v77, s74, v73 bitop3:0xe4
	v_bitop3_b32 v77, v93, s74, v74 bitop3:0xe4
	v_bfe_i32 v73, v160, 24, 1
	v_bfe_i32 v74, v161, 24, 1
	v_bitop3_b32 v93, v78, s74, v73 bitop3:0xe4
	v_bitop3_b32 v78, v94, s74, v74 bitop3:0xe4
	v_bfe_i32 v73, v160, 25, 1
	v_bfe_i32 v74, v161, 25, 1
	v_bitop3_b32 v79, v79, s74, v73 bitop3:0xe4
	v_bitop3_b32 v73, v95, s74, v74 bitop3:0xe4
	v_bfe_i32 v74, v160, 26, 1
	v_bfe_i32 v75, v161, 26, 1
	v_bitop3_b32 v80, v80, s74, v74 bitop3:0xe4
	v_bitop3_b32 v74, v96, s74, v75 bitop3:0xe4
	v_bfe_i32 v75, v160, 27, 1
	v_bfe_i32 v94, v161, 27, 1
	v_bitop3_b32 v81, v81, s74, v75 bitop3:0xe4
	v_bitop3_b32 v75, v97, s74, v94 bitop3:0xe4
	v_max_f32_e32 v94, v146, v82
	v_max3_f32 v94, v94, v83, v147
	v_max3_f32 v94, v94, v148, v149
	v_max3_f32 v94, v94, v87, v88
	v_max3_f32 v94, v94, v89, v90
	v_max3_f32 v94, v94, v91, v92
	v_max3_f32 v94, v94, v93, v79
	v_max3_f32 v94, v94, v80, v81
	v_max3_f32 v94, v94, v66, v67
	v_max3_f32 v94, v94, v68, v69
	v_max3_f32 v94, v94, v70, v71
	v_max3_f32 v94, v94, v72, v84
	v_max3_f32 v94, v94, v85, v86
	v_max3_f32 v94, v94, v76, v77
	v_max3_f32 v94, v94, v78, v73
	v_max3_f32 v94, v94, v74, v75
	v_mov_b32_e32 v95, v94
	v_mov_b32_e32 v208, 1.0
	s_nop 0
	v_permlane32_swap_b32_e32 v94, v95
	v_max_f32_e32 v94, v94, v95
	v_fmamk_f32 v95, v94, 0x3e0293ee, v190
	v_cmp_ge_f32_e32 vcc, 0x4138aa3b, v95
	s_cmp_eq_u64 vcc, exec
	s_cselect_b64 s[6:7], -1, 0
	s_cbranch_scc0 .Lp5_y1_slow

; __device__ __forceinline__ void sel_mask_tile(f32x16& p0, f32x16& p1, unsigned wlo, unsigned whi, int hi) {
;     const unsigned NEGB = 0xff800000u;
;     const unsigned lo = wlo >> (4 * hi), h2 = whi >> (4 * hi);
; #pragma unroll
;     for (int r = 0; r < 16; ++r) {
;         const int c = (r & 3) + 8 * (r >> 2);
;         const unsigned m0 = (unsigned)__builtin_amdgcn_sbfe((int)lo, c, 1), m1 = (unsigned)__builtin_amdgcn_sbfe((int)h2, c, 1);
;         p0[r] = __uint_as_float((__float_as_uint(p0[r]) & m0) | (NEGB & ~m0));
;         p1[r] = __uint_as_float((__float_as_uint(p1[r]) & m1) | (NEGB & ~m1));
;     }
; }
; __device__ __forceinline__ void partialSM(f32x16& p0, f32x16& p1, float& m_reg, float& mn, float& alpha) {
;     float pmax = p0[0];
; #pragma unroll
;     for (int r = 1; r < 16; ++r) pmax = fmaxf(pmax, p0[r]);
; #pragma unroll
;     for (int r = 0; r < 16; ++r) pmax = fmaxf(pmax, p1[r]);
;     { auto rr = __builtin_amdgcn_permlane32_swap(__float_as_uint(pmax), __float_as_uint(pmax), false, false);
;       pmax = fmaxf(__uint_as_float(rr[0]), __uint_as_float(rr[1])); }
;     constexpr float C2 = 1.4426950408889634f * SCALE;
;     if (__builtin_expect(__all((pmax - m_reg) * SCALE <= THR), 1)) { mn = m_reg; alpha = 1.f; }
;     else { mn = fmaxf(m_reg, pmax); alpha = __builtin_amdgcn_exp2f((m_reg - mn) * C2); m_reg = mn; }
.Lp5_k1_skip:
	s_waitcnt lgkmcnt(0)
	s_barrier
	s_nop 0
	s_waitcnt vmcnt(2)
	v_lshrrev_b32_e32 v193, v163, v228
	v_bfe_i32 v192, v193, 0, 1
	v_bitop3_b32 v192, v82, s74, v192 bitop3:0xe4
	v_bfe_i32 v82, v193, 1, 1
	v_bitop3_b32 v146, v83, s74, v82 bitop3:0xe4
	v_bfe_i32 v82, v193, 2, 1
	v_bitop3_b32 v147, v84, s74, v82 bitop3:0xe4
	v_bfe_i32 v82, v193, 3, 1
	v_bitop3_b32 v148, v85, s74, v82 bitop3:0xe4
	v_bfe_i32 v82, v193, 8, 1
	v_bitop3_b32 v149, v86, s74, v82 bitop3:0xe4
	v_bfe_i32 v82, v193, 9, 1
	v_bitop3_b32 v150, v87, s74, v82 bitop3:0xe4
	v_bfe_i32 v82, v193, 10, 1
	v_bitop3_b32 v88, v88, s74, v82 bitop3:0xe4
	v_bfe_i32 v82, v193, 11, 1
	v_bitop3_b32 v89, v89, s74, v82 bitop3:0xe4
	v_bfe_i32 v82, v193, 16, 1
	v_bitop3_b32 v90, v90, s74, v82 bitop3:0xe4
	v_bfe_i32 v82, v193, 17, 1
	v_bitop3_b32 v91, v91, s74, v82 bitop3:0xe4
	v_bfe_i32 v82, v193, 18, 1
	v_bitop3_b32 v92, v92, s74, v82 bitop3:0xe4
	v_bfe_i32 v82, v193, 19, 1
	v_bitop3_b32 v93, v93, s74, v82 bitop3:0xe4
	v_bfe_i32 v82, v193, 24, 1
	v_bitop3_b32 v94, v94, s74, v82 bitop3:0xe4
	v_bfe_i32 v82, v193, 25, 1
	v_bitop3_b32 v95, v95, s74, v82 bitop3:0xe4
	v_bfe_i32 v82, v193, 26, 1
	v_bitop3_b32 v96, v96, s74, v82 bitop3:0xe4
	v_bfe_i32 v82, v193, 27, 1
	v_bitop3_b32 v97, v97, s74, v82 bitop3:0xe4
	v_max_f32_e32 v82, v192, v146
	v_max3_f32 v82, v82, v147, v148
	v_max3_f32 v82, v82, v149, v150
	v_max3_f32 v82, v82, v88, v89
	v_max3_f32 v82, v82, v90, v91
	v_lshrrev_b32_e32 v194, v163, v229
	v_max3_f32 v82, v82, v92, v93
	v_bfe_i32 v195, v194, 0, 1
	v_bfe_i32 v172, v194, 1, 1
	v_max3_f32 v82, v82, v94, v95
	v_bitop3_b32 v66, v66, s74, v195 bitop3:0xe4
	v_bfe_i32 v83, v194, 2, 1
	v_bfe_i32 v84, v194, 3, 1
	v_max3_f32 v230, v82, v96, v97
	v_bitop3_b32 v67, v67, s74, v172 bitop3:0xe4
	v_bfe_i32 v85, v194, 8, 1
	v_bfe_i32 v86, v194, 9, 1
	v_bitop3_b32 v82, v68, s74, v83 bitop3:0xe4
	v_max3_f32 v68, v230, v66, v67
	v_bitop3_b32 v83, v69, s74, v84 bitop3:0xe4
	v_bfe_i32 v87, v194, 10, 1
	v_bfe_i32 v151, v194, 11, 1
	v_bitop3_b32 v84, v70, s74, v85 bitop3:0xe4
	v_max3_f32 v68, v68, v82, v83
	v_bitop3_b32 v85, v71, s74, v86 bitop3:0xe4
	v_bfe_i32 v152, v194, 16, 1
	v_bfe_i32 v153, v194, 17, 1
	v_bitop3_b32 v86, v72, s74, v87 bitop3:0xe4
	v_max3_f32 v68, v68, v84, v85
	v_bitop3_b32 v87, v73, s74, v151 bitop3:0xe4
	v_bfe_i32 v154, v194, 18, 1
	v_bfe_i32 v155, v194, 19, 1
	v_bitop3_b32 v74, v74, s74, v152 bitop3:0xe4
	v_max3_f32 v69, v68, v86, v87
	v_bitop3_b32 v75, v75, s74, v153 bitop3:0xe4
	v_bfe_i32 v156, v194, 24, 1
	v_bfe_i32 v157, v194, 25, 1
	v_bitop3_b32 v68, v76, s74, v154 bitop3:0xe4
	v_max3_f32 v71, v69, v74, v75
	v_bitop3_b32 v69, v77, s74, v155 bitop3:0xe4
	v_bfe_i32 v230, v194, 26, 1
	v_bfe_i32 v231, v194, 27, 1
	v_bitop3_b32 v70, v78, s74, v156 bitop3:0xe4
	v_max3_f32 v73, v71, v68, v69
	v_bitop3_b32 v71, v79, s74, v157 bitop3:0xe4
	v_bitop3_b32 v72, v80, s74, v230 bitop3:0xe4
	v_max3_f32 v76, v73, v70, v71
	v_bitop3_b32 v73, v81, s74, v231 bitop3:0xe4
	v_max3_f32 v76, v76, v72, v73
	v_mov_b32_e32 v77, v76
	v_mov_b32_e32 v207, 1.0
	s_nop 0
	v_permlane32_swap_b32_e32 v76, v77
	v_max_f32_e32 v76, v76, v77
	v_fmamk_f32 v77, v76, 0x3e0293ee, v190
	v_cmp_ge_f32_e32 vcc, 0x4138aa3b, v77
	s_cmp_eq_u64 vcc, exec
	s_cselect_b64 s[6:7], -1, 0
.LBB0_1307:
	s_cbranch_scc0 .Lp5_y2_slow
